# v21 plus MLA loop: remaining first-batch V fragment pairs hoisted into late QK (dead registers), P.V MFMAs 1-4 wait-free, next-tile load block moved behind P.V MFMA 4
# baseline (speedup 1.0000x reference)
; #define SBAR() __builtin_amdgcn_sched_barrier(0)
; #define SLOAD(i, k0) do { st_[i].vs = *reinterpret_cast<const bf16x8*>(&Vh[(size_t)((k0) + sr) * LDK + sc]); \
;     st_[i].ks = *reinterpret_cast<const bf16x8*>(&Kh[(size_t)((k0) + sr) * LDK + sc]); \
;     if (DQ == 96) st_[i].kr = *reinterpret_cast<const bf16x8*>(&Kr[(size_t)((k0) + sr2) * 32 + sc2]); } while (0)
; #define SWRITE(b, i) do { *(bf16x8*)(V_lds + (b) * SHM_V + vst0) = st_[i].vs; *(bf16x8*)(K_lds + (b) * SHM_K + kst0) = st_[i].ks; \
;     if (DQ == 96) { if (tid < 256) *(bf16x8*)(K_lds + (b) * SHM_K + kst2) = st_[i].kr; } } while (0)
; #define SWAIT() do { if (DQ == 96) asm volatile("s_waitcnt vmcnt(3)" ::: "memory"); else asm volatile("s_waitcnt vmcnt(2)" ::: "memory"); } while (0)
; #define SLOAD(i, k0) do { st_[i].vs = *reinterpret_cast<const bf16x8*>(&Vh[(size_t)((k0) + sr) * LDK + sc]); \
;     st_[i].ks = *reinterpret_cast<const bf16x8*>(&Kh[(size_t)((k0) + sr) * LDK + sc]); \
;     if (DQ == 96) st_[i].kr = *reinterpret_cast<const bf16x8*>(&Kr[(size_t)((k0) + sr2) * 32 + sc2]); } while (0)
; #define SWRITE(b, i) do { *(bf16x8*)(V_lds + (b) * SHM_V + vst0) = st_[i].vs; *(bf16x8*)(K_lds + (b) * SHM_K + kst0) = st_[i].ks; \
;     if (DQ == 96) { if (tid < 256) *(bf16x8*)(K_lds + (b) * SHM_K + kst2) = st_[i].kr; } } while (0)
; #define SWAIT() do { if (DQ == 96) asm volatile("s_waitcnt vmcnt(3)" ::: "memory"); else asm volatile("s_waitcnt vmcnt(2)" ::: "memory"); } while (0)
; template <int DQ, bool WIN, int LDQ, int LDK> ...
;     ...
;         SBAR(); qkt<DQ>(pB0, pB1, K_lds + SHM_K, qr, minit, r32, hi);
;         finish(pA0, pA1); SBAR();
;         SLOAD(SO, KBASE(j + 2)); SBAR();
;         pv(vb0);
;         __syncthreads(); SWAIT(); SWRITE(0, SE);
;         lsum_upd();
.LBB0_1094:
	ds_read_b64_tr_b16 v[40:41], v194 offset:0
	ds_read_b64_tr_b16 v[42:43], v194 offset:0x400
	ds_read_b64_tr_b16 v[44:45], v194 offset:0x800
	ds_read_b64_tr_b16 v[46:47], v194 offset:0xc00
	ds_read_b128 v[198:201], v191 offset:36352
	ds_read_b128 v[80:83], v191 offset:29696
	ds_read_b128 v[202:205], v191 offset:29728
	v_exp_f32_e32 v72, v72
	v_exp_f32_e32 v73, v73
	v_exp_f32_e32 v74, v74
	s_waitcnt lgkmcnt(1)
	v_mfma_f32_32x32x16_bf16 v[96:111], v[80:83], v[134:137], v[48:63]
	v_exp_f32_e32 v75, v75
	v_exp_f32_e32 v197, v64
	v_exp_f32_e32 v206, v77
	v_exp_f32_e32 v207, v78
	v_exp_f32_e32 v208, v79
	v_mfma_f32_32x32x16_bf16 v[80:95], v[198:201], v[134:137], v[48:63]
	ds_read_b128 v[198:201], v191 offset:36384
	s_waitcnt lgkmcnt(1)
	v_mfma_f32_32x32x16_bf16 v[96:111], v[202:205], v[130:133], v[96:111]
	s_waitcnt lgkmcnt(0)
	v_mfma_f32_32x32x16_bf16 v[80:95], v[198:201], v[130:133], v[80:95]
	ds_read_b128 v[198:201], v191 offset:29760
	ds_read_b128 v[202:205], v191 offset:36416
	s_waitcnt lgkmcnt(1)
	v_mfma_f32_32x32x16_bf16 v[96:111], v[198:201], v[126:129], v[96:111]
	s_waitcnt lgkmcnt(0)
	v_mfma_f32_32x32x16_bf16 v[80:95], v[202:205], v[126:129], v[80:95]
	ds_read_b128 v[198:201], v191 offset:29792
	ds_read_b128 v[202:205], v191 offset:36448
	s_waitcnt lgkmcnt(1)
	v_mfma_f32_32x32x16_bf16 v[96:111], v[198:201], v[122:125], v[96:111]
	s_waitcnt lgkmcnt(0)
	v_mfma_f32_32x32x16_bf16 v[80:95], v[202:205], v[122:125], v[80:95]
	ds_read_b128 v[198:201], v191 offset:29824
	ds_read_b128 v[202:205], v191 offset:36480
	s_waitcnt lgkmcnt(1)
	v_mfma_f32_32x32x16_bf16 v[96:111], v[198:201], v[118:121], v[96:111]
	s_waitcnt lgkmcnt(0)
	v_mfma_f32_32x32x16_bf16 v[80:95], v[202:205], v[118:121], v[80:95]
	ds_read_b64_tr_b16 v[212:213], v194 offset:0x1000
	ds_read_b64_tr_b16 v[214:215], v194 offset:0x1400
	ds_read_b64_tr_b16 v[216:217], v194 offset:0x1800
	ds_read_b64_tr_b16 v[218:219], v194 offset:0x1c00
	ds_read_b128 v[198:201], v191 offset:29856
	ds_read_b128 v[202:205], v191 offset:36512
	s_waitcnt lgkmcnt(1)
	v_mfma_f32_32x32x16_bf16 v[96:111], v[198:201], v[114:117], v[96:111]
	v_exp_f32_e32 v198, v65
	v_exp_f32_e32 v199, v66
	v_exp_f32_e32 v200, v67
	v_exp_f32_e32 v201, v68
	v_cvt_pk_bf16_f32 v68, v161, v196
	s_waitcnt lgkmcnt(0)
	v_mfma_f32_32x32x16_bf16 v[80:95], v[202:205], v[114:117], v[80:95]
	v_exp_f32_e32 v202, v69
	v_exp_f32_e32 v203, v70
	v_exp_f32_e32 v204, v71
	v_exp_f32_e32 v205, v76
	v_cvt_pk_bf16_f32 v69, v158, v168
	v_cvt_pk_bf16_f32 v70, v159, v169
	v_cvt_pk_bf16_f32 v71, v160, v195
	v_cvt_pk_bf16_f32 v64, v150, v154
	v_cvt_pk_bf16_f32 v65, v151, v155
	v_cvt_pk_bf16_f32 v66, v152, v156
	v_cvt_pk_bf16_f32 v67, v153, v157
	v_cvt_pk_bf16_f32 v76, v197, v198
	v_cvt_pk_bf16_f32 v77, v199, v200
	v_cvt_pk_bf16_f32 v78, v201, v202
	v_cvt_pk_bf16_f32 v79, v203, v204
	v_cvt_pk_bf16_f32 v72, v72, v73
	v_cvt_pk_bf16_f32 v73, v74, v75
	v_cvt_pk_bf16_f32 v74, v205, v206
	v_cvt_pk_bf16_f32 v75, v207, v208
	v_lshl_add_u64 v[168:169], s[26:27], 0, v[164:165]
	s_mov_b32 s4, 0x218c0000
	v_add_co_u32_e32 v150, vcc, s4, v168
	s_nop 1
	v_addc_co_u32_e32 v151, vcc, 0, v169, vcc
	global_load_dwordx4 v[154:157], v[150:151], off offset:128
	global_load_dwordx4 v[158:161], v[150:151], off
	v_lshl_add_u64 v[150:151], s[26:27], 0, v[166:167]
	global_load_dwordx4 v[150:153], v[150:151], off
	ds_read_b64_tr_b16 v[196:197], v194 offset:0x200
	ds_read_b64_tr_b16 v[198:199], v194 offset:0x600
	ds_read_b64_tr_b16 v[200:201], v194 offset:0xa00
	ds_read_b64_tr_b16 v[202:203], v194 offset:0xe00
	ds_read_b64_tr_b16 v[204:205], v194 offset:0x1200
	ds_read_b64_tr_b16 v[206:207], v194 offset:0x1600
	ds_read_b64_tr_b16 v[208:209], v194 offset:0x1a00
	ds_read_b64_tr_b16 v[210:211], v194 offset:0x1e00
	v_mfma_f32_32x32x16_bf16 v[0:15], v[68:71], v[40:43], v[0:15]
	v_mfma_f32_32x32x16_bf16 v[0:15], v[64:67], v[44:47], v[0:15]
	v_mfma_f32_32x32x16_bf16 v[0:15], v[76:79], v[212:215], v[0:15]
	v_mfma_f32_32x32x16_bf16 v[0:15], v[72:75], v[216:219], v[0:15]
	s_waitcnt lgkmcnt(0)
	v_mfma_f32_32x32x16_bf16 v[16:31], v[68:71], v[196:199], v[16:31]
	s_waitcnt vmcnt(3)
	ds_write_b128 v192, v[138:141]
	ds_write_b128 v193, v[142:145] offset:16384
	v_mfma_f32_32x32x16_bf16 v[16:31], v[64:67], v[200:203], v[16:31]
	v_mfma_f32_32x32x16_bf16 v[16:31], v[76:79], v[204:207], v[16:31]
	v_mfma_f32_32x32x16_bf16 v[16:31], v[72:75], v[208:211], v[16:31]
	ds_write_b128 v112, v[146:149] offset:16512
; #define SBAR() __builtin_amdgcn_sched_barrier(0)
; #define SLOAD(i, k0) do { st_[i].vs = *reinterpret_cast<const bf16x8*>(&Vh[(size_t)((k0) + sr) * LDK + sc]); \
;     st_[i].ks = *reinterpret_cast<const bf16x8*>(&Kh[(size_t)((k0) + sr) * LDK + sc]); \
;     if (DQ == 96) st_[i].kr = *reinterpret_cast<const bf16x8*>(&Kr[(size_t)((k0) + sr2) * 32 + sc2]); } while (0)
; #define SWRITE(b, i) do { *(bf16x8*)(V_lds + (b) * SHM_V + vst0) = st_[i].vs; *(bf16x8*)(K_lds + (b) * SHM_K + kst0) = st_[i].ks; \
;     if (DQ == 96) { if (tid < 256) *(bf16x8*)(K_lds + (b) * SHM_K + kst2) = st_[i].kr; } } while (0)
; #define SWAIT() do { if (DQ == 96) asm volatile("s_waitcnt vmcnt(3)" ::: "memory"); else asm volatile("s_waitcnt vmcnt(2)" ::: "memory"); } while (0)
; #define SLOAD(i, k0) do { st_[i].vs = *reinterpret_cast<const bf16x8*>(&Vh[(size_t)((k0) + sr) * LDK + sc]); \
;     st_[i].ks = *reinterpret_cast<const bf16x8*>(&Kh[(size_t)((k0) + sr) * LDK + sc]); \
;     if (DQ == 96) st_[i].kr = *reinterpret_cast<const bf16x8*>(&Kr[(size_t)((k0) + sr2) * 32 + sc2]); } while (0)
; #define SWRITE(b, i) do { *(bf16x8*)(V_lds + (b) * SHM_V + vst0) = st_[i].vs; *(bf16x8*)(K_lds + (b) * SHM_K + kst0) = st_[i].ks; \
;     if (DQ == 96) { if (tid < 256) *(bf16x8*)(K_lds + (b) * SHM_K + kst2) = st_[i].kr; } } while (0)
; #define SWAIT() do { if (DQ == 96) asm volatile("s_waitcnt vmcnt(3)" ::: "memory"); else asm volatile("s_waitcnt vmcnt(2)" ::: "memory"); } while (0)
; template <int DQ, bool WIN, int LDQ, int LDK> ...
;     ...
;         SBAR(); qkt<DQ>(pA0, pA1, K_lds, qr, minit, r32, hi);
;         finish(pB0, pB1); SBAR();
;         if (j + 3 < NT) SLOAD(SE, KBASE(j + 3)); SBAR();
;         pv(vb0 + SHM_V);
;         __syncthreads(); SWAIT(); SWRITE(1, SO);
;         lsum_upd();
.LBB0_1096:
	s_add_i32 s17, s17, 2
	v_exp_f32_e32 v195, v96
	v_mfma_f32_16x16x32_bf16 v[32:35], v[68:71], v[36:39], v[32:35]
	v_exp_f32_e32 v204, v97
	v_exp_f32_e32 v205, v98
	v_exp_f32_e32 v206, v99
	v_exp_f32_e32 v207, v100
	v_exp_f32_e32 v208, v101
	v_exp_f32_e32 v209, v102
	v_exp_f32_e32 v210, v103
	v_mfma_f32_16x16x32_bf16 v[32:35], v[64:67], v[36:39], v[32:35]
	v_exp_f32_e32 v211, v104
	v_exp_f32_e32 v212, v105
	v_exp_f32_e32 v213, v106
	v_exp_f32_e32 v214, v107
	v_exp_f32_e32 v215, v108
	v_exp_f32_e32 v216, v109
	v_exp_f32_e32 v217, v110
	v_mfma_f32_16x16x32_bf16 v[32:35], v[76:79], v[36:39], v[32:35]
	v_exp_f32_e32 v218, v111
	s_waitcnt lgkmcnt(0)
	s_barrier
	v_mfma_f32_16x16x32_bf16 v[32:35], v[72:75], v[36:39], v[32:35]
	ds_read_b64_tr_b16 v[40:41], v190 offset:0
	ds_read_b64_tr_b16 v[42:43], v190 offset:0x400
	ds_read_b64_tr_b16 v[44:45], v190 offset:0x800
	ds_read_b64_tr_b16 v[46:47], v190 offset:0xc00
	ds_read_b128 v[196:199], v191 offset:23040
	ds_read_b128 v[64:67], v191 offset:16384
	ds_read_b128 v[200:203], v191 offset:16416
	v_exp_f32_e32 v95, v95
	v_exp_f32_e32 v219, v88
	v_exp_f32_e32 v220, v89
	s_waitcnt lgkmcnt(1)
	v_mfma_f32_32x32x16_bf16 v[96:111], v[64:67], v[134:137], v[48:63]
	v_exp_f32_e32 v221, v90
	v_exp_f32_e32 v222, v91
	v_exp_f32_e32 v223, v92
	v_exp_f32_e32 v224, v93
	v_exp_f32_e32 v225, v94
	v_mfma_f32_32x32x16_bf16 v[64:79], v[196:199], v[134:137], v[48:63]
	ds_read_b128 v[196:199], v191 offset:23072
	s_waitcnt lgkmcnt(1)
	v_mfma_f32_32x32x16_bf16 v[96:111], v[200:203], v[130:133], v[96:111]
	s_waitcnt lgkmcnt(0)
	v_mfma_f32_32x32x16_bf16 v[64:79], v[196:199], v[130:133], v[64:79]
	ds_read_b128 v[196:199], v191 offset:16448
	ds_read_b128 v[200:203], v191 offset:23104
	s_waitcnt lgkmcnt(1)
	v_mfma_f32_32x32x16_bf16 v[96:111], v[196:199], v[126:129], v[96:111]
	s_waitcnt lgkmcnt(0)
	v_mfma_f32_32x32x16_bf16 v[64:79], v[200:203], v[126:129], v[64:79]
	ds_read_b128 v[196:199], v191 offset:16480
	ds_read_b128 v[200:203], v191 offset:23136
	s_waitcnt lgkmcnt(1)
	v_mfma_f32_32x32x16_bf16 v[96:111], v[196:199], v[122:125], v[96:111]
	s_waitcnt lgkmcnt(0)
	v_mfma_f32_32x32x16_bf16 v[64:79], v[200:203], v[122:125], v[64:79]
	ds_read_b128 v[196:199], v191 offset:16512
	ds_read_b128 v[200:203], v191 offset:23168
	s_waitcnt lgkmcnt(1)
	v_mfma_f32_32x32x16_bf16 v[96:111], v[196:199], v[118:121], v[96:111]
	s_waitcnt lgkmcnt(0)
	v_mfma_f32_32x32x16_bf16 v[64:79], v[200:203], v[118:121], v[64:79]
	ds_read_b64_tr_b16 v[138:139], v190 offset:0x1000
	ds_read_b64_tr_b16 v[140:141], v190 offset:0x1400
	ds_read_b64_tr_b16 v[142:143], v190 offset:0x1800
	ds_read_b64_tr_b16 v[144:145], v190 offset:0x1c00
	ds_read_b128 v[196:199], v191 offset:16544
	ds_read_b128 v[200:203], v191 offset:23200
	s_waitcnt lgkmcnt(1)
	v_mfma_f32_32x32x16_bf16 v[96:111], v[196:199], v[114:117], v[96:111]
	v_exp_f32_e32 v196, v80
	v_exp_f32_e32 v197, v81
	v_exp_f32_e32 v198, v82
	v_exp_f32_e32 v199, v83
	v_cvt_pk_bf16_f32 v80, v195, v204
	v_cvt_pk_bf16_f32 v81, v205, v206
	v_cvt_pk_bf16_f32 v82, v207, v208
	s_waitcnt lgkmcnt(0)
	v_mfma_f32_32x32x16_bf16 v[64:79], v[200:203], v[114:117], v[64:79]
	v_exp_f32_e32 v200, v84
	v_exp_f32_e32 v201, v85
	v_exp_f32_e32 v202, v86
	v_exp_f32_e32 v203, v87
	v_cvt_pk_bf16_f32 v83, v209, v210
	v_cvt_pk_bf16_f32 v84, v211, v212
	v_cvt_pk_bf16_f32 v85, v213, v214
	v_cvt_pk_bf16_f32 v86, v215, v216
	v_cvt_pk_bf16_f32 v87, v217, v218
	v_cvt_pk_bf16_f32 v88, v196, v197
	v_cvt_pk_bf16_f32 v89, v198, v199
	v_cvt_pk_bf16_f32 v90, v200, v201
	v_cvt_pk_bf16_f32 v91, v202, v203
	v_cvt_pk_bf16_f32 v92, v219, v220
	v_cvt_pk_bf16_f32 v93, v221, v222
	v_cvt_pk_bf16_f32 v94, v223, v224
	v_cvt_pk_bf16_f32 v95, v225, v95
.LBB0_1098:
	ds_read_b64_tr_b16 v[196:197], v190 offset:0x200
	ds_read_b64_tr_b16 v[198:199], v190 offset:0x600
	ds_read_b64_tr_b16 v[200:201], v190 offset:0xa00
	ds_read_b64_tr_b16 v[202:203], v190 offset:0xe00
	ds_read_b64_tr_b16 v[204:205], v190 offset:0x1200
	ds_read_b64_tr_b16 v[206:207], v190 offset:0x1600
	ds_read_b64_tr_b16 v[208:209], v190 offset:0x1a00
	ds_read_b64_tr_b16 v[210:211], v190 offset:0x1e00
	v_mfma_f32_32x32x16_bf16 v[0:15], v[80:83], v[40:43], v[0:15]
	v_mfma_f32_32x32x16_bf16 v[0:15], v[84:87], v[44:47], v[0:15]
	v_mfma_f32_32x32x16_bf16 v[0:15], v[88:91], v[138:141], v[0:15]
	v_mfma_f32_32x32x16_bf16 v[0:15], v[92:95], v[142:145], v[0:15]
	v_add_co_u32_e32 v142, vcc, 0x21900000, v168
	s_waitcnt vmcnt(3)
	v_lshl_add_u64 v[146:147], s[26:27], 0, v[162:163]
	v_addc_co_u32_e32 v143, vcc, 0, v169, vcc
	global_load_dwordx4 v[138:141], v[142:143], off offset:128
	s_nop 0
	global_load_dwordx4 v[142:145], v[142:143], off
	s_nop 0
	global_load_dwordx4 v[146:149], v[146:147], off
	s_waitcnt lgkmcnt(0)
	v_mfma_f32_32x32x16_bf16 v[16:31], v[80:83], v[196:199], v[16:31]
	s_waitcnt vmcnt(3)
	ds_write_b128 v192, v[154:157] offset:8192
	ds_write_b128 v193, v[158:161] offset:29696
	v_mfma_f32_32x32x16_bf16 v[16:31], v[84:87], v[200:203], v[16:31]
	v_mfma_f32_32x32x16_bf16 v[16:31], v[88:91], v[204:207], v[16:31]
	v_mfma_f32_32x32x16_bf16 v[16:31], v[92:95], v[208:211], v[16:31]
	ds_write_b128 v112, v[150:153] offset:29824
	s_branch .LBB0_1093
